# v86 + weight-transpose items issue all 32 row loads before the first wait (one HBM round trip per item instead of four)
# baseline (speedup 1.0000x reference)
.LBB0_192:
	v_lshl_add_u64 v[20:21], v[16:17], 0, s[6:7]
	v_lshl_add_u64 v[22:23], v[14:15], 0, s[6:7]
	v_lshl_add_u64 v[24:25], v[12:13], 0, s[6:7]
	v_lshl_add_u64 v[26:27], v[10:11], 0, s[6:7]
	v_lshl_add_u64 v[28:29], v[8:9], 0, s[6:7]
	v_lshl_add_u64 v[30:31], v[6:7], 0, s[6:7]
	v_lshl_add_u64 v[32:33], v[4:5], 0, s[6:7]
	v_lshl_add_u64 v[34:35], v[2:3], 0, s[6:7]
	global_load_dword v100, v[20:21], off nt
	global_load_dword v101, v[22:23], off nt
	global_load_dword v102, v[24:25], off nt
	global_load_dword v103, v[26:27], off nt
	global_load_dword v104, v[28:29], off nt
	global_load_dword v105, v[30:31], off nt
	global_load_dword v106, v[32:33], off nt
	global_load_dword v107, v[34:35], off nt
	s_add_u32 s6, s6, 0x10000
	s_addc_u32 s7, s7, 0
	v_lshl_add_u64 v[20:21], v[16:17], 0, s[6:7]
	v_lshl_add_u64 v[22:23], v[14:15], 0, s[6:7]
	v_lshl_add_u64 v[24:25], v[12:13], 0, s[6:7]
	v_lshl_add_u64 v[26:27], v[10:11], 0, s[6:7]
	v_lshl_add_u64 v[28:29], v[8:9], 0, s[6:7]
	v_lshl_add_u64 v[30:31], v[6:7], 0, s[6:7]
	v_lshl_add_u64 v[32:33], v[4:5], 0, s[6:7]
	v_lshl_add_u64 v[34:35], v[2:3], 0, s[6:7]
	global_load_dword v108, v[20:21], off nt
	global_load_dword v109, v[22:23], off nt
	global_load_dword v110, v[24:25], off nt
	global_load_dword v111, v[26:27], off nt
	global_load_dword v112, v[28:29], off nt
	global_load_dword v113, v[30:31], off nt
	global_load_dword v114, v[32:33], off nt
	global_load_dword v115, v[34:35], off nt
	s_add_u32 s6, s6, 0x10000
	s_addc_u32 s7, s7, 0
	v_lshl_add_u64 v[20:21], v[16:17], 0, s[6:7]
	v_lshl_add_u64 v[22:23], v[14:15], 0, s[6:7]
	v_lshl_add_u64 v[24:25], v[12:13], 0, s[6:7]
	v_lshl_add_u64 v[26:27], v[10:11], 0, s[6:7]
	v_lshl_add_u64 v[28:29], v[8:9], 0, s[6:7]
	v_lshl_add_u64 v[30:31], v[6:7], 0, s[6:7]
	v_lshl_add_u64 v[32:33], v[4:5], 0, s[6:7]
	v_lshl_add_u64 v[34:35], v[2:3], 0, s[6:7]
	global_load_dword v116, v[20:21], off nt
	global_load_dword v117, v[22:23], off nt
	global_load_dword v118, v[24:25], off nt
	global_load_dword v119, v[26:27], off nt
	global_load_dword v120, v[28:29], off nt
	global_load_dword v121, v[30:31], off nt
	global_load_dword v122, v[32:33], off nt
	global_load_dword v123, v[34:35], off nt
	s_add_u32 s6, s6, 0x10000
	s_addc_u32 s7, s7, 0
	v_lshl_add_u64 v[20:21], v[16:17], 0, s[6:7]
	v_lshl_add_u64 v[22:23], v[14:15], 0, s[6:7]
	v_lshl_add_u64 v[24:25], v[12:13], 0, s[6:7]
	v_lshl_add_u64 v[26:27], v[10:11], 0, s[6:7]
	v_lshl_add_u64 v[28:29], v[8:9], 0, s[6:7]
	v_lshl_add_u64 v[30:31], v[6:7], 0, s[6:7]
	v_lshl_add_u64 v[32:33], v[4:5], 0, s[6:7]
	v_lshl_add_u64 v[34:35], v[2:3], 0, s[6:7]
	global_load_dword v124, v[20:21], off nt
	global_load_dword v125, v[22:23], off nt
	global_load_dword v126, v[24:25], off nt
	global_load_dword v127, v[26:27], off nt
	global_load_dword v128, v[28:29], off nt
	global_load_dword v129, v[30:31], off nt
	global_load_dword v130, v[32:33], off nt
	global_load_dword v131, v[34:35], off nt
	s_add_u32 s6, s6, 0x10000
	s_addc_u32 s7, s7, 0
	s_waitcnt vmcnt(30)
	ds_write2_b32 v19, v100, v101 offset1:66
	s_waitcnt vmcnt(28)
	ds_write2_b32 v19, v102, v103 offset0:132 offset1:198
	v_add_u32_e32 v27, 0x400, v19
	s_waitcnt vmcnt(26)
	ds_write2_b32 v27, v104, v105 offset0:8 offset1:74
	s_waitcnt vmcnt(24)
	ds_write2_b32 v27, v106, v107 offset0:140 offset1:206
	v_add_u32_e32 v19, 0x840, v19
	s_waitcnt vmcnt(22)
	ds_write2_b32 v19, v108, v109 offset1:66
	s_waitcnt vmcnt(20)
	ds_write2_b32 v19, v110, v111 offset0:132 offset1:198
	v_add_u32_e32 v27, 0x400, v19
	s_waitcnt vmcnt(18)
	ds_write2_b32 v27, v112, v113 offset0:8 offset1:74
	s_waitcnt vmcnt(16)
	ds_write2_b32 v27, v114, v115 offset0:140 offset1:206
	v_add_u32_e32 v19, 0x840, v19
	s_waitcnt vmcnt(14)
	ds_write2_b32 v19, v116, v117 offset1:66
	s_waitcnt vmcnt(12)
	ds_write2_b32 v19, v118, v119 offset0:132 offset1:198
	v_add_u32_e32 v27, 0x400, v19
	s_waitcnt vmcnt(10)
	ds_write2_b32 v27, v120, v121 offset0:8 offset1:74
	s_waitcnt vmcnt(8)
	ds_write2_b32 v27, v122, v123 offset0:140 offset1:206
	v_add_u32_e32 v19, 0x840, v19
	s_waitcnt vmcnt(6)
	ds_write2_b32 v19, v124, v125 offset1:66
	s_waitcnt vmcnt(4)
	ds_write2_b32 v19, v126, v127 offset0:132 offset1:198
	v_add_u32_e32 v27, 0x400, v19
	s_waitcnt vmcnt(2)
	ds_write2_b32 v27, v128, v129 offset0:8 offset1:74
	s_waitcnt vmcnt(0)
	ds_write2_b32 v27, v130, v131 offset0:140 offset1:206
	v_add_u32_e32 v19, 0x840, v19
	v_lshlrev_b32_e32 v0, 3, v18
	v_lshrrev_b32_e32 v24, 3, v18
	v_and_b32_e32 v0, 56, v0
	s_waitcnt lgkmcnt(0)
	v_mul_u32_u24_e32 v2, 0x84, v0
	v_lshlrev_b32_e32 v3, 2, v24
	v_add3_u32 v26, s2, v2, v3
	s_and_b32 s4, s9, 0x7fffffc0
	ds_read2_b32 v[6:7], v26 offset1:8
	s_addk_i32 s4, 0xe400
	ds_read2_b32 v[10:11], v26 offset0:33 offset1:41
	s_lshl_b64 s[6:7], s[4:5], 1
	s_add_u32 s6, s90, s6
	ds_read2_b32 v[12:13], v26 offset0:66 offset1:74
	s_addc_u32 s7, s92, s7
	v_lshlrev_b32_e32 v0, 1, v0
	ds_read2_b32 v[14:15], v26 offset0:99 offset1:107
	v_lshl_add_u64 v[8:9], s[6:7], 0, v[0:1]
	s_waitcnt lgkmcnt(3)
	v_bfe_u32 v0, v6, 16, 1
	v_add3_u32 v0, v6, v0, s13
	s_waitcnt lgkmcnt(2)
	v_bfe_u32 v2, v10, 16, 1
	ds_read2_b32 v[16:17], v26 offset0:132 offset1:140
	v_lshrrev_b32_e32 v0, 16, v0
	v_add3_u32 v2, v10, v2, s13
	ds_read2_b32 v[18:19], v26 offset0:165 offset1:173
	v_and_or_b32 v2, v2, s14, v0
	s_waitcnt lgkmcnt(3)
	v_bfe_u32 v0, v12, 16, 1
	v_add3_u32 v0, v12, v0, s13
	s_waitcnt lgkmcnt(2)
	v_bfe_u32 v3, v14, 16, 1
	ds_read2_b32 v[20:21], v26 offset0:198 offset1:206
	v_lshrrev_b32_e32 v0, 16, v0
	v_add3_u32 v3, v14, v3, s13
	ds_read2_b32 v[22:23], v26 offset0:231 offset1:239
	v_and_or_b32 v3, v3, s14, v0
	s_waitcnt lgkmcnt(3)
	v_bfe_u32 v0, v16, 16, 1
	v_add3_u32 v0, v16, v0, s13
	s_waitcnt lgkmcnt(2)
	v_bfe_u32 v4, v18, 16, 1
	v_lshrrev_b32_e32 v0, 16, v0
	v_add3_u32 v4, v18, v4, s13
	v_and_or_b32 v4, v4, s14, v0
	s_waitcnt lgkmcnt(1)
	v_bfe_u32 v0, v20, 16, 1
	v_add3_u32 v0, v20, v0, s13
	s_waitcnt lgkmcnt(0)
	v_bfe_u32 v5, v22, 16, 1
	v_lshrrev_b32_e32 v0, 16, v0
	v_add3_u32 v5, v22, v5, s13
	v_and_or_b32 v5, v5, s14, v0
	v_or_b32_e32 v0, s8, v24
	v_lshlrev_b32_e32 v0, 12, v0
	v_lshl_add_u64 v[24:25], v[8:9], 0, v[0:1]
	global_store_dwordx4 v[24:25], v[2:5], off
	v_bfe_u32 v6, v23, 16, 1
	v_add3_u32 v6, v23, v6, s13
	v_bfe_u32 v2, v7, 16, 1
	v_add3_u32 v2, v7, v2, s13
	v_bfe_u32 v3, v11, 16, 1
	v_lshrrev_b32_e32 v2, 16, v2
	v_add3_u32 v3, v11, v3, s13
	v_and_or_b32 v2, v3, s14, v2
	v_bfe_u32 v3, v13, 16, 1
	v_add3_u32 v3, v13, v3, s13
	v_bfe_u32 v4, v15, 16, 1
	v_lshrrev_b32_e32 v3, 16, v3
	v_add3_u32 v4, v15, v4, s13
	v_and_or_b32 v3, v4, s14, v3
	v_bfe_u32 v4, v17, 16, 1
	v_add3_u32 v4, v17, v4, s13
	v_bfe_u32 v5, v19, 16, 1
	v_lshrrev_b32_e32 v4, 16, v4
	v_add3_u32 v5, v19, v5, s13
	v_and_or_b32 v4, v5, s14, v4
	v_bfe_u32 v5, v21, 16, 1
	v_add3_u32 v5, v21, v5, s13
	v_lshrrev_b32_e32 v5, 16, v5
	v_and_or_b32 v5, v6, s14, v5
	v_or_b32_e32 v6, 0x8000, v0
	v_mov_b32_e32 v7, v1
	ds_read2_b32 v[10:11], v26 offset0:16 offset1:24
	v_lshl_add_u64 v[6:7], v[8:9], 0, v[6:7]
	global_store_dwordx4 v[6:7], v[2:5], off
	ds_read2_b32 v[6:7], v26 offset0:49 offset1:57
	ds_read2_b32 v[12:13], v26 offset0:82 offset1:90
	ds_read2_b32 v[14:15], v26 offset0:115 offset1:123
	s_waitcnt lgkmcnt(3)
	v_bfe_u32 v2, v10, 16, 1
	v_add3_u32 v2, v10, v2, s13
	s_waitcnt lgkmcnt(2)
	v_bfe_u32 v3, v6, 16, 1
	ds_read2_b32 v[16:17], v26 offset0:148 offset1:156
	v_lshrrev_b32_e32 v2, 16, v2
	v_add3_u32 v3, v6, v3, s13
	ds_read2_b32 v[18:19], v26 offset0:181 offset1:189
	v_and_or_b32 v2, v3, s14, v2
	s_waitcnt lgkmcnt(3)
	v_bfe_u32 v3, v12, 16, 1
	v_add3_u32 v3, v12, v3, s13
	s_waitcnt lgkmcnt(2)
	v_bfe_u32 v4, v14, 16, 1
	ds_read2_b32 v[20:21], v26 offset0:214 offset1:222
	v_lshrrev_b32_e32 v3, 16, v3
	v_add3_u32 v4, v14, v4, s13
	ds_read2_b32 v[22:23], v26 offset0:247 offset1:255
	v_and_or_b32 v3, v4, s14, v3
	s_waitcnt lgkmcnt(3)
	v_bfe_u32 v4, v16, 16, 1
	v_add3_u32 v4, v16, v4, s13
	s_waitcnt lgkmcnt(2)
	v_bfe_u32 v5, v18, 16, 1
	v_lshrrev_b32_e32 v4, 16, v4
	v_add3_u32 v5, v18, v5, s13
	v_and_or_b32 v4, v5, s14, v4
	s_waitcnt lgkmcnt(1)
	v_bfe_u32 v5, v20, 16, 1
	v_add3_u32 v5, v20, v5, s13
	s_waitcnt lgkmcnt(0)
	v_bfe_u32 v6, v22, 16, 1
	v_lshrrev_b32_e32 v5, 16, v5
	v_add3_u32 v6, v22, v6, s13
	v_or_b32_e32 v24, 0x10000, v0
	v_mov_b32_e32 v25, v1
	v_and_or_b32 v5, v6, s14, v5
	v_lshl_add_u64 v[24:25], v[8:9], 0, v[24:25]
	global_store_dwordx4 v[24:25], v[2:5], off
	v_bfe_u32 v6, v23, 16, 1
	v_add3_u32 v6, v23, v6, s13
	v_bfe_u32 v2, v11, 16, 1
	v_add3_u32 v2, v11, v2, s13
	v_bfe_u32 v3, v7, 16, 1
	v_lshrrev_b32_e32 v2, 16, v2
	v_add3_u32 v3, v7, v3, s13
	v_and_or_b32 v2, v3, s14, v2
	v_bfe_u32 v3, v13, 16, 1
	v_add3_u32 v3, v13, v3, s13
	v_bfe_u32 v4, v15, 16, 1
	v_lshrrev_b32_e32 v3, 16, v3
	v_add3_u32 v4, v15, v4, s13
	v_and_or_b32 v3, v4, s14, v3
	v_bfe_u32 v4, v17, 16, 1
	v_add3_u32 v4, v17, v4, s13
	v_bfe_u32 v5, v19, 16, 1
	v_lshrrev_b32_e32 v4, 16, v4
	v_add3_u32 v5, v19, v5, s13
	v_and_or_b32 v4, v5, s14, v4
	v_bfe_u32 v5, v21, 16, 1
	v_add3_u32 v5, v21, v5, s13
	v_lshrrev_b32_e32 v5, 16, v5
	v_or_b32_e32 v0, 0x18000, v0
	v_and_or_b32 v5, v6, s14, v5
	v_lshl_add_u64 v[6:7], v[8:9], 0, v[0:1]
	global_store_dwordx4 v[6:7], v[2:5], off
	s_waitcnt lgkmcnt(0)
	s_mov_b64 s[6:7], 0

.LBB0_196:
	v_lshl_add_u64 v[20:21], v[16:17], 0, s[6:7]
	v_lshl_add_u64 v[22:23], v[14:15], 0, s[6:7]
	v_lshl_add_u64 v[24:25], v[12:13], 0, s[6:7]
	v_lshl_add_u64 v[26:27], v[10:11], 0, s[6:7]
	v_lshl_add_u64 v[28:29], v[8:9], 0, s[6:7]
	v_lshl_add_u64 v[30:31], v[6:7], 0, s[6:7]
	v_lshl_add_u64 v[32:33], v[4:5], 0, s[6:7]
	v_lshl_add_u64 v[34:35], v[2:3], 0, s[6:7]
	global_load_dword v100, v[20:21], off nt
	global_load_dword v101, v[22:23], off nt
	global_load_dword v102, v[24:25], off nt
	global_load_dword v103, v[26:27], off nt
	global_load_dword v104, v[28:29], off nt
	global_load_dword v105, v[30:31], off nt
	global_load_dword v106, v[32:33], off nt
	global_load_dword v107, v[34:35], off nt
	s_add_u32 s6, s6, 0x10000
	s_addc_u32 s7, s7, 0
	v_lshl_add_u64 v[20:21], v[16:17], 0, s[6:7]
	v_lshl_add_u64 v[22:23], v[14:15], 0, s[6:7]
	v_lshl_add_u64 v[24:25], v[12:13], 0, s[6:7]
	v_lshl_add_u64 v[26:27], v[10:11], 0, s[6:7]
	v_lshl_add_u64 v[28:29], v[8:9], 0, s[6:7]
	v_lshl_add_u64 v[30:31], v[6:7], 0, s[6:7]
	v_lshl_add_u64 v[32:33], v[4:5], 0, s[6:7]
	v_lshl_add_u64 v[34:35], v[2:3], 0, s[6:7]
	global_load_dword v108, v[20:21], off nt
	global_load_dword v109, v[22:23], off nt
	global_load_dword v110, v[24:25], off nt
	global_load_dword v111, v[26:27], off nt
	global_load_dword v112, v[28:29], off nt
	global_load_dword v113, v[30:31], off nt
	global_load_dword v114, v[32:33], off nt
	global_load_dword v115, v[34:35], off nt
	s_add_u32 s6, s6, 0x10000
	s_addc_u32 s7, s7, 0
	v_lshl_add_u64 v[20:21], v[16:17], 0, s[6:7]
	v_lshl_add_u64 v[22:23], v[14:15], 0, s[6:7]
	v_lshl_add_u64 v[24:25], v[12:13], 0, s[6:7]
	v_lshl_add_u64 v[26:27], v[10:11], 0, s[6:7]
	v_lshl_add_u64 v[28:29], v[8:9], 0, s[6:7]
	v_lshl_add_u64 v[30:31], v[6:7], 0, s[6:7]
	v_lshl_add_u64 v[32:33], v[4:5], 0, s[6:7]
	v_lshl_add_u64 v[34:35], v[2:3], 0, s[6:7]
	global_load_dword v116, v[20:21], off nt
	global_load_dword v117, v[22:23], off nt
	global_load_dword v118, v[24:25], off nt
	global_load_dword v119, v[26:27], off nt
	global_load_dword v120, v[28:29], off nt
	global_load_dword v121, v[30:31], off nt
	global_load_dword v122, v[32:33], off nt
	global_load_dword v123, v[34:35], off nt
	s_add_u32 s6, s6, 0x10000
	s_addc_u32 s7, s7, 0
	v_lshl_add_u64 v[20:21], v[16:17], 0, s[6:7]
	v_lshl_add_u64 v[22:23], v[14:15], 0, s[6:7]
	v_lshl_add_u64 v[24:25], v[12:13], 0, s[6:7]
	v_lshl_add_u64 v[26:27], v[10:11], 0, s[6:7]
	v_lshl_add_u64 v[28:29], v[8:9], 0, s[6:7]
	v_lshl_add_u64 v[30:31], v[6:7], 0, s[6:7]
	v_lshl_add_u64 v[32:33], v[4:5], 0, s[6:7]
	v_lshl_add_u64 v[34:35], v[2:3], 0, s[6:7]
	global_load_dword v124, v[20:21], off nt
	global_load_dword v125, v[22:23], off nt
	global_load_dword v126, v[24:25], off nt
	global_load_dword v127, v[26:27], off nt
	global_load_dword v128, v[28:29], off nt
	global_load_dword v129, v[30:31], off nt
	global_load_dword v130, v[32:33], off nt
	global_load_dword v131, v[34:35], off nt
	s_add_u32 s6, s6, 0x10000
	s_addc_u32 s7, s7, 0
	s_waitcnt vmcnt(30)
	ds_write2_b32 v19, v100, v101 offset1:66
	s_waitcnt vmcnt(28)
	ds_write2_b32 v19, v102, v103 offset0:132 offset1:198
	v_add_u32_e32 v27, 0x400, v19
	s_waitcnt vmcnt(26)
	ds_write2_b32 v27, v104, v105 offset0:8 offset1:74
	s_waitcnt vmcnt(24)
	ds_write2_b32 v27, v106, v107 offset0:140 offset1:206
	v_add_u32_e32 v19, 0x840, v19
	s_waitcnt vmcnt(22)
	ds_write2_b32 v19, v108, v109 offset1:66
	s_waitcnt vmcnt(20)
	ds_write2_b32 v19, v110, v111 offset0:132 offset1:198
	v_add_u32_e32 v27, 0x400, v19
	s_waitcnt vmcnt(18)
	ds_write2_b32 v27, v112, v113 offset0:8 offset1:74
	s_waitcnt vmcnt(16)
	ds_write2_b32 v27, v114, v115 offset0:140 offset1:206
	v_add_u32_e32 v19, 0x840, v19
	s_waitcnt vmcnt(14)
	ds_write2_b32 v19, v116, v117 offset1:66
	s_waitcnt vmcnt(12)
	ds_write2_b32 v19, v118, v119 offset0:132 offset1:198
	v_add_u32_e32 v27, 0x400, v19
	s_waitcnt vmcnt(10)
	ds_write2_b32 v27, v120, v121 offset0:8 offset1:74
	s_waitcnt vmcnt(8)
	ds_write2_b32 v27, v122, v123 offset0:140 offset1:206
	v_add_u32_e32 v19, 0x840, v19
	s_waitcnt vmcnt(6)
	ds_write2_b32 v19, v124, v125 offset1:66
	s_waitcnt vmcnt(4)
	ds_write2_b32 v19, v126, v127 offset0:132 offset1:198
	v_add_u32_e32 v27, 0x400, v19
	s_waitcnt vmcnt(2)
	ds_write2_b32 v27, v128, v129 offset0:8 offset1:74
	s_waitcnt vmcnt(0)
	ds_write2_b32 v27, v130, v131 offset0:140 offset1:206
	v_add_u32_e32 v19, 0x840, v19
	v_lshlrev_b32_e32 v0, 3, v18
	v_lshrrev_b32_e32 v24, 3, v18
	v_and_b32_e32 v0, 56, v0
	s_waitcnt lgkmcnt(0)
	v_mul_u32_u24_e32 v2, 0x84, v0
	v_lshlrev_b32_e32 v3, 2, v24
	v_add3_u32 v26, s2, v2, v3
	s_and_b32 s4, s9, 0x1fc0
	ds_read2_b32 v[6:7], v26 offset1:8
	s_addk_i32 s4, 0xe800
	ds_read2_b32 v[10:11], v26 offset0:33 offset1:41
	s_lshl_b64 s[6:7], s[4:5], 1
	s_add_u32 s6, s94, s6
	ds_read2_b32 v[12:13], v26 offset0:66 offset1:74
	s_addc_u32 s7, s33, s7
	v_lshlrev_b32_e32 v0, 1, v0
	ds_read2_b32 v[14:15], v26 offset0:99 offset1:107
	v_lshl_add_u64 v[8:9], s[6:7], 0, v[0:1]
	s_waitcnt lgkmcnt(3)
	v_bfe_u32 v0, v6, 16, 1
	v_add3_u32 v0, v6, v0, s13
	s_waitcnt lgkmcnt(2)
	v_bfe_u32 v2, v10, 16, 1
	ds_read2_b32 v[16:17], v26 offset0:132 offset1:140
	v_lshrrev_b32_e32 v0, 16, v0
	v_add3_u32 v2, v10, v2, s13
	ds_read2_b32 v[18:19], v26 offset0:165 offset1:173
	v_and_or_b32 v2, v2, s14, v0
	s_waitcnt lgkmcnt(3)
	v_bfe_u32 v0, v12, 16, 1
	v_add3_u32 v0, v12, v0, s13
	s_waitcnt lgkmcnt(2)
	v_bfe_u32 v3, v14, 16, 1
	ds_read2_b32 v[20:21], v26 offset0:198 offset1:206
	v_lshrrev_b32_e32 v0, 16, v0
	v_add3_u32 v3, v14, v3, s13
	ds_read2_b32 v[22:23], v26 offset0:231 offset1:239
	v_and_or_b32 v3, v3, s14, v0
	s_waitcnt lgkmcnt(3)
	v_bfe_u32 v0, v16, 16, 1
	v_add3_u32 v0, v16, v0, s13
	s_waitcnt lgkmcnt(2)
	v_bfe_u32 v4, v18, 16, 1
	v_lshrrev_b32_e32 v0, 16, v0
	v_add3_u32 v4, v18, v4, s13
	v_and_or_b32 v4, v4, s14, v0
	s_waitcnt lgkmcnt(1)
	v_bfe_u32 v0, v20, 16, 1
	v_add3_u32 v0, v20, v0, s13
	s_waitcnt lgkmcnt(0)
	v_bfe_u32 v5, v22, 16, 1
	v_lshrrev_b32_e32 v0, 16, v0
	v_add3_u32 v5, v22, v5, s13
	v_and_or_b32 v5, v5, s14, v0
	v_or_b32_e32 v0, s8, v24
	v_lshlrev_b32_e32 v0, 11, v0
	v_lshl_add_u64 v[24:25], v[8:9], 0, v[0:1]
	global_store_dwordx4 v[24:25], v[2:5], off
	v_bfe_u32 v6, v23, 16, 1
	v_add3_u32 v6, v23, v6, s13
	v_bfe_u32 v2, v7, 16, 1
	v_add3_u32 v2, v7, v2, s13
	v_bfe_u32 v3, v11, 16, 1
	v_lshrrev_b32_e32 v2, 16, v2
	v_add3_u32 v3, v11, v3, s13
	v_and_or_b32 v2, v3, s14, v2
	v_bfe_u32 v3, v13, 16, 1
	v_add3_u32 v3, v13, v3, s13
	v_bfe_u32 v4, v15, 16, 1
	v_lshrrev_b32_e32 v3, 16, v3
	v_add3_u32 v4, v15, v4, s13
	v_and_or_b32 v3, v4, s14, v3
	v_bfe_u32 v4, v17, 16, 1
	v_add3_u32 v4, v17, v4, s13
	v_bfe_u32 v5, v19, 16, 1
	v_lshrrev_b32_e32 v4, 16, v4
	v_add3_u32 v5, v19, v5, s13
	v_and_or_b32 v4, v5, s14, v4
	v_bfe_u32 v5, v21, 16, 1
	v_add3_u32 v5, v21, v5, s13
	v_lshrrev_b32_e32 v5, 16, v5
	v_and_or_b32 v5, v6, s14, v5
	v_or_b32_e32 v6, 0x4000, v0
	v_mov_b32_e32 v7, v1
	ds_read2_b32 v[10:11], v26 offset0:16 offset1:24
	v_lshl_add_u64 v[6:7], v[8:9], 0, v[6:7]
	global_store_dwordx4 v[6:7], v[2:5], off
	ds_read2_b32 v[6:7], v26 offset0:49 offset1:57
	ds_read2_b32 v[12:13], v26 offset0:82 offset1:90
	ds_read2_b32 v[14:15], v26 offset0:115 offset1:123
	s_waitcnt lgkmcnt(3)
	v_bfe_u32 v2, v10, 16, 1
	v_add3_u32 v2, v10, v2, s13
	s_waitcnt lgkmcnt(2)
	v_bfe_u32 v3, v6, 16, 1
	ds_read2_b32 v[16:17], v26 offset0:148 offset1:156
	v_lshrrev_b32_e32 v2, 16, v2
	v_add3_u32 v3, v6, v3, s13
	ds_read2_b32 v[18:19], v26 offset0:181 offset1:189
	v_and_or_b32 v2, v3, s14, v2
	s_waitcnt lgkmcnt(3)
	v_bfe_u32 v3, v12, 16, 1
	v_add3_u32 v3, v12, v3, s13
	s_waitcnt lgkmcnt(2)
	v_bfe_u32 v4, v14, 16, 1
	ds_read2_b32 v[20:21], v26 offset0:214 offset1:222
	v_lshrrev_b32_e32 v3, 16, v3
	v_add3_u32 v4, v14, v4, s13
	ds_read2_b32 v[22:23], v26 offset0:247 offset1:255
	v_and_or_b32 v3, v4, s14, v3
	s_waitcnt lgkmcnt(3)
	v_bfe_u32 v4, v16, 16, 1
	v_add3_u32 v4, v16, v4, s13
	s_waitcnt lgkmcnt(2)
	v_bfe_u32 v5, v18, 16, 1
	v_lshrrev_b32_e32 v4, 16, v4
	v_add3_u32 v5, v18, v5, s13
	v_and_or_b32 v4, v5, s14, v4
	s_waitcnt lgkmcnt(1)
	v_bfe_u32 v5, v20, 16, 1
	v_add3_u32 v5, v20, v5, s13
	s_waitcnt lgkmcnt(0)
	v_bfe_u32 v6, v22, 16, 1
	v_lshrrev_b32_e32 v5, 16, v5
	v_add3_u32 v6, v22, v6, s13
	v_or_b32_e32 v24, 0x8000, v0
	v_mov_b32_e32 v25, v1
	v_and_or_b32 v5, v6, s14, v5
	v_lshl_add_u64 v[24:25], v[8:9], 0, v[24:25]
	global_store_dwordx4 v[24:25], v[2:5], off
	v_bfe_u32 v6, v23, 16, 1
	v_add3_u32 v6, v23, v6, s13
	v_bfe_u32 v2, v11, 16, 1
	v_add3_u32 v2, v11, v2, s13
	v_bfe_u32 v3, v7, 16, 1
	v_lshrrev_b32_e32 v2, 16, v2
	v_add3_u32 v3, v7, v3, s13
	v_and_or_b32 v2, v3, s14, v2
	v_bfe_u32 v3, v13, 16, 1
	v_add3_u32 v3, v13, v3, s13
	v_bfe_u32 v4, v15, 16, 1
	v_lshrrev_b32_e32 v3, 16, v3
	v_add3_u32 v4, v15, v4, s13
	v_and_or_b32 v3, v4, s14, v3
	v_bfe_u32 v4, v17, 16, 1
	v_add3_u32 v4, v17, v4, s13
	v_bfe_u32 v5, v19, 16, 1
	v_lshrrev_b32_e32 v4, 16, v4
	v_add3_u32 v5, v19, v5, s13
	v_and_or_b32 v4, v5, s14, v4
	v_bfe_u32 v5, v21, 16, 1
	v_add3_u32 v5, v21, v5, s13
	v_lshrrev_b32_e32 v5, 16, v5
	v_or_b32_e32 v0, 0xc000, v0
	v_and_or_b32 v5, v6, s14, v5
	v_lshl_add_u64 v[6:7], v[8:9], 0, v[0:1]
	global_store_dwordx4 v[6:7], v[2:5], off
	s_waitcnt lgkmcnt(0)

.LBB0_201:
	v_lshl_add_u64 v[20:21], v[16:17], 0, s[8:9]
	v_lshl_add_u64 v[22:23], v[14:15], 0, s[8:9]
	v_lshl_add_u64 v[24:25], v[12:13], 0, s[8:9]
	v_lshl_add_u64 v[26:27], v[10:11], 0, s[8:9]
	v_lshl_add_u64 v[28:29], v[8:9], 0, s[8:9]
	v_lshl_add_u64 v[30:31], v[6:7], 0, s[8:9]
	v_lshl_add_u64 v[32:33], v[4:5], 0, s[8:9]
	v_lshl_add_u64 v[34:35], v[2:3], 0, s[8:9]
	global_load_dword v100, v[20:21], off nt
	global_load_dword v101, v[22:23], off nt
	global_load_dword v102, v[24:25], off nt
	global_load_dword v103, v[26:27], off nt
	global_load_dword v104, v[28:29], off nt
	global_load_dword v105, v[30:31], off nt
	global_load_dword v106, v[32:33], off nt
	global_load_dword v107, v[34:35], off nt
	s_add_u32 s8, s8, 0x60000
	s_addc_u32 s9, s9, 0
	v_lshl_add_u64 v[20:21], v[16:17], 0, s[8:9]
	v_lshl_add_u64 v[22:23], v[14:15], 0, s[8:9]
	v_lshl_add_u64 v[24:25], v[12:13], 0, s[8:9]
	v_lshl_add_u64 v[26:27], v[10:11], 0, s[8:9]
	v_lshl_add_u64 v[28:29], v[8:9], 0, s[8:9]
	v_lshl_add_u64 v[30:31], v[6:7], 0, s[8:9]
	v_lshl_add_u64 v[32:33], v[4:5], 0, s[8:9]
	v_lshl_add_u64 v[34:35], v[2:3], 0, s[8:9]
	global_load_dword v108, v[20:21], off nt
	global_load_dword v109, v[22:23], off nt
	global_load_dword v110, v[24:25], off nt
	global_load_dword v111, v[26:27], off nt
	global_load_dword v112, v[28:29], off nt
	global_load_dword v113, v[30:31], off nt
	global_load_dword v114, v[32:33], off nt
	global_load_dword v115, v[34:35], off nt
	s_add_u32 s8, s8, 0x60000
	s_addc_u32 s9, s9, 0
	v_lshl_add_u64 v[20:21], v[16:17], 0, s[8:9]
	v_lshl_add_u64 v[22:23], v[14:15], 0, s[8:9]
	v_lshl_add_u64 v[24:25], v[12:13], 0, s[8:9]
	v_lshl_add_u64 v[26:27], v[10:11], 0, s[8:9]
	v_lshl_add_u64 v[28:29], v[8:9], 0, s[8:9]
	v_lshl_add_u64 v[30:31], v[6:7], 0, s[8:9]
	v_lshl_add_u64 v[32:33], v[4:5], 0, s[8:9]
	v_lshl_add_u64 v[34:35], v[2:3], 0, s[8:9]
	global_load_dword v116, v[20:21], off nt
	global_load_dword v117, v[22:23], off nt
	global_load_dword v118, v[24:25], off nt
	global_load_dword v119, v[26:27], off nt
	global_load_dword v120, v[28:29], off nt
	global_load_dword v121, v[30:31], off nt
	global_load_dword v122, v[32:33], off nt
	global_load_dword v123, v[34:35], off nt
	s_add_u32 s8, s8, 0x60000
	s_addc_u32 s9, s9, 0
	v_lshl_add_u64 v[20:21], v[16:17], 0, s[8:9]
	v_lshl_add_u64 v[22:23], v[14:15], 0, s[8:9]
	v_lshl_add_u64 v[24:25], v[12:13], 0, s[8:9]
	v_lshl_add_u64 v[26:27], v[10:11], 0, s[8:9]
	v_lshl_add_u64 v[28:29], v[8:9], 0, s[8:9]
	v_lshl_add_u64 v[30:31], v[6:7], 0, s[8:9]
	v_lshl_add_u64 v[32:33], v[4:5], 0, s[8:9]
	v_lshl_add_u64 v[34:35], v[2:3], 0, s[8:9]
	global_load_dword v124, v[20:21], off nt
	global_load_dword v125, v[22:23], off nt
	global_load_dword v126, v[24:25], off nt
	global_load_dword v127, v[26:27], off nt
	global_load_dword v128, v[28:29], off nt
	global_load_dword v129, v[30:31], off nt
	global_load_dword v130, v[32:33], off nt
	global_load_dword v131, v[34:35], off nt
	s_add_u32 s8, s8, 0x60000
	s_addc_u32 s9, s9, 0
	s_waitcnt vmcnt(30)
	ds_write2_b32 v19, v100, v101 offset1:66
	s_waitcnt vmcnt(28)
	ds_write2_b32 v19, v102, v103 offset0:132 offset1:198
	v_add_u32_e32 v27, 0x400, v19
	s_waitcnt vmcnt(26)
	ds_write2_b32 v27, v104, v105 offset0:8 offset1:74
	s_waitcnt vmcnt(24)
	ds_write2_b32 v27, v106, v107 offset0:140 offset1:206
	v_add_u32_e32 v19, 0x840, v19
	s_waitcnt vmcnt(22)
	ds_write2_b32 v19, v108, v109 offset1:66
	s_waitcnt vmcnt(20)
	ds_write2_b32 v19, v110, v111 offset0:132 offset1:198
	v_add_u32_e32 v27, 0x400, v19
	s_waitcnt vmcnt(18)
	ds_write2_b32 v27, v112, v113 offset0:8 offset1:74
	s_waitcnt vmcnt(16)
	ds_write2_b32 v27, v114, v115 offset0:140 offset1:206
	v_add_u32_e32 v19, 0x840, v19
	s_waitcnt vmcnt(14)
	ds_write2_b32 v19, v116, v117 offset1:66
	s_waitcnt vmcnt(12)
	ds_write2_b32 v19, v118, v119 offset0:132 offset1:198
	v_add_u32_e32 v27, 0x400, v19
	s_waitcnt vmcnt(10)
	ds_write2_b32 v27, v120, v121 offset0:8 offset1:74
	s_waitcnt vmcnt(8)
	ds_write2_b32 v27, v122, v123 offset0:140 offset1:206
	v_add_u32_e32 v19, 0x840, v19
	s_waitcnt vmcnt(6)
	ds_write2_b32 v19, v124, v125 offset1:66
	s_waitcnt vmcnt(4)
	ds_write2_b32 v19, v126, v127 offset0:132 offset1:198
	v_add_u32_e32 v27, 0x400, v19
	s_waitcnt vmcnt(2)
	ds_write2_b32 v27, v128, v129 offset0:8 offset1:74
	s_waitcnt vmcnt(0)
	ds_write2_b32 v27, v130, v131 offset0:140 offset1:206
	v_add_u32_e32 v19, 0x840, v19
	v_lshlrev_b32_e32 v0, 3, v18
	v_lshrrev_b32_e32 v24, 3, v18
	v_and_b32_e32 v0, 56, v0
	s_waitcnt lgkmcnt(0)
	v_mul_u32_u24_e32 v2, 0x84, v0
	v_lshlrev_b32_e32 v3, 2, v24
	v_add3_u32 v28, s2, v2, v3
	ds_read2_b32 v[6:7], v28 offset1:8
	s_ashr_i32 s7, s6, 31
	ds_read2_b32 v[10:11], v28 offset0:33 offset1:41
	s_lshl_b64 s[6:7], s[6:7], 1
	s_add_u32 s6, s82, s6
	ds_read2_b32 v[12:13], v28 offset0:66 offset1:74
	s_addc_u32 s7, s83, s7
	v_lshlrev_b32_e32 v0, 1, v0
	ds_read2_b32 v[14:15], v28 offset0:99 offset1:107
	v_lshl_add_u64 v[8:9], s[6:7], 0, v[0:1]
	s_waitcnt lgkmcnt(3)
	v_bfe_u32 v0, v6, 16, 1
	v_add3_u32 v0, v6, v0, s13
	s_waitcnt lgkmcnt(2)
	v_bfe_u32 v2, v10, 16, 1
	ds_read2_b32 v[16:17], v28 offset0:132 offset1:140
	v_lshrrev_b32_e32 v0, 16, v0
	v_add3_u32 v2, v10, v2, s13
	ds_read2_b32 v[18:19], v28 offset0:165 offset1:173
	v_and_or_b32 v2, v2, s14, v0
	s_waitcnt lgkmcnt(3)
	v_bfe_u32 v0, v12, 16, 1
	v_add3_u32 v0, v12, v0, s13
	s_waitcnt lgkmcnt(2)
	v_bfe_u32 v3, v14, 16, 1
	ds_read2_b32 v[20:21], v28 offset0:198 offset1:206
	v_lshrrev_b32_e32 v0, 16, v0
	v_add3_u32 v3, v14, v3, s13
	ds_read2_b32 v[22:23], v28 offset0:231 offset1:239
	v_and_or_b32 v3, v3, s14, v0
	s_waitcnt lgkmcnt(3)
	v_bfe_u32 v0, v16, 16, 1
	v_add3_u32 v0, v16, v0, s13
	s_waitcnt lgkmcnt(2)
	v_bfe_u32 v4, v18, 16, 1
	v_lshrrev_b32_e32 v0, 16, v0
	v_add3_u32 v4, v18, v4, s13
	v_and_or_b32 v4, v4, s14, v0
	s_waitcnt lgkmcnt(1)
	v_bfe_u32 v0, v20, 16, 1
	v_or_b32_e32 v24, s4, v24
	v_add3_u32 v0, v20, v0, s13
	s_waitcnt lgkmcnt(0)
	v_bfe_u32 v5, v22, 16, 1
	v_ashrrev_i32_e32 v25, 31, v24
	v_lshrrev_b32_e32 v0, 16, v0
	v_add3_u32 v5, v22, v5, s13
	v_lshlrev_b64 v[26:27], 11, v[24:25]
	v_and_or_b32 v5, v5, s14, v0
	v_lshl_add_u64 v[26:27], v[8:9], 0, v[26:27]
	v_bfe_u32 v0, v7, 16, 1
	global_store_dwordx4 v[26:27], v[2:5], off
	v_add3_u32 v0, v7, v0, s13
	v_lshrrev_b32_e32 v0, 16, v0
	v_bfe_u32 v2, v11, 16, 1
	v_add3_u32 v2, v11, v2, s13
	v_and_or_b32 v2, v2, s14, v0
	v_bfe_u32 v0, v13, 16, 1
	v_add3_u32 v0, v13, v0, s13
	v_bfe_u32 v3, v15, 16, 1
	v_lshrrev_b32_e32 v0, 16, v0
	v_add3_u32 v3, v15, v3, s13
	v_and_or_b32 v3, v3, s14, v0
	v_bfe_u32 v0, v17, 16, 1
	v_add3_u32 v0, v17, v0, s13
	v_bfe_u32 v4, v19, 16, 1
	v_lshrrev_b32_e32 v0, 16, v0
	v_add3_u32 v4, v19, v4, s13
	v_and_or_b32 v4, v4, s14, v0
	v_bfe_u32 v0, v21, 16, 1
	v_or_b32_e32 v6, 8, v24
	v_add3_u32 v0, v21, v0, s13
	v_bfe_u32 v5, v23, 16, 1
	v_ashrrev_i32_e32 v7, 31, v6
	v_lshrrev_b32_e32 v0, 16, v0
	v_add3_u32 v5, v23, v5, s13
	v_lshlrev_b64 v[6:7], 11, v[6:7]
	v_and_or_b32 v5, v5, s14, v0
	ds_read2_b32 v[10:11], v28 offset0:16 offset1:24
	v_lshl_add_u64 v[6:7], v[8:9], 0, v[6:7]
	global_store_dwordx4 v[6:7], v[2:5], off
	ds_read2_b32 v[6:7], v28 offset0:49 offset1:57
	ds_read2_b32 v[12:13], v28 offset0:82 offset1:90
	ds_read2_b32 v[14:15], v28 offset0:115 offset1:123
	s_waitcnt lgkmcnt(3)
	v_bfe_u32 v0, v10, 16, 1
	v_add3_u32 v0, v10, v0, s13
	s_waitcnt lgkmcnt(2)
	v_bfe_u32 v2, v6, 16, 1
	ds_read2_b32 v[16:17], v28 offset0:148 offset1:156
	v_lshrrev_b32_e32 v0, 16, v0
	v_add3_u32 v2, v6, v2, s13
	ds_read2_b32 v[18:19], v28 offset0:181 offset1:189
	v_and_or_b32 v2, v2, s14, v0
	s_waitcnt lgkmcnt(3)
	v_bfe_u32 v0, v12, 16, 1
	v_add3_u32 v0, v12, v0, s13
	s_waitcnt lgkmcnt(2)
	v_bfe_u32 v3, v14, 16, 1
	ds_read2_b32 v[20:21], v28 offset0:214 offset1:222
	v_lshrrev_b32_e32 v0, 16, v0
	v_add3_u32 v3, v14, v3, s13
	ds_read2_b32 v[22:23], v28 offset0:247 offset1:255
	v_and_or_b32 v3, v3, s14, v0
	s_waitcnt lgkmcnt(3)
	v_bfe_u32 v0, v16, 16, 1
	v_add3_u32 v0, v16, v0, s13
	s_waitcnt lgkmcnt(2)
	v_bfe_u32 v4, v18, 16, 1
	v_lshrrev_b32_e32 v0, 16, v0
	v_add3_u32 v4, v18, v4, s13
	v_and_or_b32 v4, v4, s14, v0
	s_waitcnt lgkmcnt(1)
	v_bfe_u32 v0, v20, 16, 1
	v_or_b32_e32 v26, 16, v24
	v_add3_u32 v0, v20, v0, s13
	s_waitcnt lgkmcnt(0)
	v_bfe_u32 v5, v22, 16, 1
	v_ashrrev_i32_e32 v27, 31, v26
	v_lshrrev_b32_e32 v0, 16, v0
	v_add3_u32 v5, v22, v5, s13
	v_lshlrev_b64 v[26:27], 11, v[26:27]
	v_and_or_b32 v5, v5, s14, v0
	v_lshl_add_u64 v[26:27], v[8:9], 0, v[26:27]
	v_bfe_u32 v0, v11, 16, 1
	global_store_dwordx4 v[26:27], v[2:5], off
	v_add3_u32 v0, v11, v0, s13
	v_lshrrev_b32_e32 v0, 16, v0
	v_bfe_u32 v2, v7, 16, 1
	v_add3_u32 v2, v7, v2, s13
	v_and_or_b32 v2, v2, s14, v0
	v_bfe_u32 v0, v13, 16, 1
	v_add3_u32 v0, v13, v0, s13
	v_bfe_u32 v3, v15, 16, 1
	v_lshrrev_b32_e32 v0, 16, v0
	v_add3_u32 v3, v15, v3, s13
	v_and_or_b32 v3, v3, s14, v0
	v_bfe_u32 v0, v17, 16, 1
	v_add3_u32 v0, v17, v0, s13
	v_bfe_u32 v4, v19, 16, 1
	v_lshrrev_b32_e32 v0, 16, v0
	v_add3_u32 v4, v19, v4, s13
	v_and_or_b32 v4, v4, s14, v0
	v_bfe_u32 v0, v21, 16, 1
	v_or_b32_e32 v6, 24, v24
	v_add3_u32 v0, v21, v0, s13
	v_bfe_u32 v5, v23, 16, 1
	v_ashrrev_i32_e32 v7, 31, v6
	v_lshrrev_b32_e32 v0, 16, v0
	v_add3_u32 v5, v23, v5, s13
	v_lshlrev_b64 v[6:7], 11, v[6:7]
	v_and_or_b32 v5, v5, s14, v0
	v_lshl_add_u64 v[6:7], v[8:9], 0, v[6:7]
	global_store_dwordx4 v[6:7], v[2:5], off
	s_waitcnt lgkmcnt(0)
	s_branch .LBB0_188
